# byte-phase pin: GEMM K loop heads aligned to 64 B (s_nop fill)
# speedup vs baseline: 1.0052x; 1.0052x over previous
.LBB0_130:
	s_ashr_i32 s13, s12, 31
	s_lshl_b64 s[14:15], s[12:13], 19
	v_readlane_b32 s16, v254, 39
	v_readlane_b32 s17, v254, 40
	s_add_u32 s14, s16, s14
	s_addc_u32 s15, s17, s15
	s_and_b64 s[16:17], s[0:1], exec
	s_cselect_b32 s13, s15, s19
	s_cselect_b32 s42, s14, s18
	s_ashr_i32 s11, s10, 31
	s_lshl_b64 s[16:17], s[10:11], 19
	s_add_u32 s16, s24, s16
	s_addc_u32 s17, s25, s17
	s_and_b64 s[22:23], s[0:1], exec
	s_cselect_b32 s11, s17, s21
	s_cselect_b32 s43, s16, s20
	s_add_u32 s18, s18, 0x40080
	s_addc_u32 s19, s19, 0
	s_add_u32 s44, s20, 0x100
	s_addc_u32 s45, s21, 0
	s_mov_b32 s46, -2
	ds_read_b128 v[152:155], v148
	ds_read_b128 v[156:159], v148 offset:1024
	ds_read_b128 v[160:163], v148 offset:2048
	ds_read_b128 v[164:167], v148 offset:3072
	ds_read_b128 v[168:171], v149
	ds_read_b128 v[172:175], v149 offset:1024
	ds_read_b128 v[176:179], v149 offset:2048
	ds_read_b128 v[180:183], v149 offset:3072
	s_add_u32 s20, s18, 0xfffc0080
	s_addc_u32 s21, s19, -1
	s_cmp_eq_u32 s46, 12
	s_cselect_b32 s23, s13, s21
	s_cselect_b32 s22, s42, s20
	s_cselect_b32 s21, s11, s45
	s_cselect_b32 s20, s43, s44
	s_add_i32 m0, s9, 0xc000
	ds_read_b128 v[184:187], v150
	ds_read_b128 v[188:191], v150 offset:1024
	ds_read_b128 v[192:195], v150 offset:2048
	ds_read_b128 v[196:199], v150 offset:3072
	ds_read_b128 v[200:203], v150 offset:4096
	ds_read_b128 v[204:207], v150 offset:5120
	ds_read_b128 v[208:211], v150 offset:6144
	ds_read_b128 v[212:215], v150 offset:7168
	global_load_lds_dwordx4 v136, s[18:19]
	s_add_i32 m0, s9, 0xe000
	s_nop 0
	global_load_lds_dwordx4 v138, s[18:19]
	s_waitcnt vmcnt(8)
	s_waitcnt lgkmcnt(0)
	s_barrier
	s_setprio 1
	s_waitcnt lgkmcnt(0)
	v_mfma_f32_16x16x32_bf16 v[124:127], v[152:155], v[184:187], 0
	v_mfma_f32_16x16x32_bf16 v[120:123], v[160:163], v[184:187], 0
	v_mfma_f32_16x16x32_bf16 v[116:119], v[152:155], v[192:195], 0
	v_mfma_f32_16x16x32_bf16 v[112:115], v[160:163], v[192:195], 0
	v_mfma_f32_16x16x32_bf16 v[100:103], v[152:155], v[200:203], 0
	v_mfma_f32_16x16x32_bf16 v[96:99], v[160:163], v[200:203], 0
	v_mfma_f32_16x16x32_bf16 v[84:87], v[152:155], v[208:211], 0
	v_mfma_f32_16x16x32_bf16 v[80:83], v[160:163], v[208:211], 0
	v_mfma_f32_16x16x32_bf16 v[124:127], v[156:159], v[188:191], v[124:127]
	v_mfma_f32_16x16x32_bf16 v[120:123], v[164:167], v[188:191], v[120:123]
	v_mfma_f32_16x16x32_bf16 v[116:119], v[156:159], v[196:199], v[116:119]
	v_mfma_f32_16x16x32_bf16 v[112:115], v[164:167], v[196:199], v[112:115]
	v_mfma_f32_16x16x32_bf16 v[100:103], v[156:159], v[204:207], v[100:103]
	v_mfma_f32_16x16x32_bf16 v[96:99], v[164:167], v[204:207], v[96:99]
	v_mfma_f32_16x16x32_bf16 v[84:87], v[156:159], v[212:215], v[84:87]
	v_mfma_f32_16x16x32_bf16 v[80:83], v[164:167], v[212:215], v[80:83]
	s_setprio 0
	s_setprio 1
	v_mfma_f32_16x16x32_bf16 v[108:111], v[168:171], v[184:187], 0
	v_mfma_f32_16x16x32_bf16 v[104:107], v[176:179], v[184:187], 0
	v_mfma_f32_16x16x32_bf16 v[92:95], v[168:171], v[192:195], 0
	v_mfma_f32_16x16x32_bf16 v[88:91], v[176:179], v[192:195], 0
	v_mfma_f32_16x16x32_bf16 v[76:79], v[168:171], v[200:203], 0
	v_mfma_f32_16x16x32_bf16 v[72:75], v[176:179], v[200:203], 0
	v_mfma_f32_16x16x32_bf16 v[68:71], v[168:171], v[208:211], 0
	v_mfma_f32_16x16x32_bf16 v[64:67], v[176:179], v[208:211], 0
	v_mfma_f32_16x16x32_bf16 v[108:111], v[172:175], v[188:191], v[108:111]
	v_mfma_f32_16x16x32_bf16 v[104:107], v[180:183], v[188:191], v[104:107]
	v_mfma_f32_16x16x32_bf16 v[92:95], v[172:175], v[196:199], v[92:95]
	v_mfma_f32_16x16x32_bf16 v[88:91], v[180:183], v[196:199], v[88:91]
	v_mfma_f32_16x16x32_bf16 v[76:79], v[172:175], v[204:207], v[76:79]
	v_mfma_f32_16x16x32_bf16 v[72:75], v[180:183], v[204:207], v[72:75]
	v_mfma_f32_16x16x32_bf16 v[68:71], v[172:175], v[212:215], v[68:71]
	v_mfma_f32_16x16x32_bf16 v[64:67], v[180:183], v[212:215], v[64:67]
	s_setprio 0
	s_barrier
	s_add_i32 s47, s38, s26
	s_mov_b32 m0, s47
	ds_read_b128 v[184:187], v150 offset:16384
	ds_read_b128 v[188:191], v150 offset:17408
	ds_read_b128 v[192:195], v150 offset:18432
	ds_read_b128 v[196:199], v150 offset:19456
	ds_read_b128 v[200:203], v150 offset:20480
	ds_read_b128 v[204:207], v150 offset:21504
	ds_read_b128 v[208:211], v150 offset:22528
	ds_read_b128 v[212:215], v150 offset:23552
	global_load_lds_dwordx4 v132, s[20:21]
	s_add_i32 m0, s47, 0x2000
	s_add_u32 s48, s20, 0x40000
	s_addc_u32 s49, s21, 0
	s_add_i32 s47, s39, s26
	global_load_lds_dwordx4 v128, s[20:21]
	s_mov_b32 m0, s47
	s_nop 0
	global_load_lds_dwordx4 v132, s[48:49]
	s_add_i32 m0, s47, 0x2000
	s_nop 0
	global_load_lds_dwordx4 v128, s[48:49]
	s_mov_b32 m0, s9
	s_nop 0
	global_load_lds_dwordx4 v134, s[22:23]
	s_mov_b32 m0, s29
	s_nop 0
	global_load_lds_dwordx4 v130, s[22:23]
	s_add_u32 s84, s20, s4
	s_addc_u32 s85, s21, s5
	s_add_u32 s86, s22, s4
	s_addc_u32 s87, s23, s5
	s_waitcnt vmcnt(8)
	s_waitcnt lgkmcnt(0)
	s_barrier
	s_setprio 1
	s_waitcnt lgkmcnt(0)
	v_mfma_f32_16x16x32_bf16 v[60:63], v[152:155], v[184:187], 0
	v_mfma_f32_16x16x32_bf16 v[56:59], v[160:163], v[184:187], 0
	v_mfma_f32_16x16x32_bf16 v[52:55], v[152:155], v[192:195], 0
	v_mfma_f32_16x16x32_bf16 v[48:51], v[160:163], v[192:195], 0
	v_mfma_f32_16x16x32_bf16 v[36:39], v[152:155], v[200:203], 0
	v_mfma_f32_16x16x32_bf16 v[32:35], v[160:163], v[200:203], 0
	v_mfma_f32_16x16x32_bf16 v[20:23], v[152:155], v[208:211], 0
	v_mfma_f32_16x16x32_bf16 v[16:19], v[160:163], v[208:211], 0
	v_mfma_f32_16x16x32_bf16 v[60:63], v[156:159], v[188:191], v[60:63]
	v_mfma_f32_16x16x32_bf16 v[56:59], v[164:167], v[188:191], v[56:59]
	v_mfma_f32_16x16x32_bf16 v[52:55], v[156:159], v[196:199], v[52:55]
	v_mfma_f32_16x16x32_bf16 v[48:51], v[164:167], v[196:199], v[48:51]
	v_mfma_f32_16x16x32_bf16 v[36:39], v[156:159], v[204:207], v[36:39]
	v_mfma_f32_16x16x32_bf16 v[32:35], v[164:167], v[204:207], v[32:35]
	v_mfma_f32_16x16x32_bf16 v[20:23], v[156:159], v[212:215], v[20:23]
	v_mfma_f32_16x16x32_bf16 v[16:19], v[164:167], v[212:215], v[16:19]
	s_setprio 0
	s_setprio 1
	v_mfma_f32_16x16x32_bf16 v[44:47], v[168:171], v[184:187], 0
	v_mfma_f32_16x16x32_bf16 v[40:43], v[176:179], v[184:187], 0
	v_mfma_f32_16x16x32_bf16 v[28:31], v[168:171], v[192:195], 0
	v_mfma_f32_16x16x32_bf16 v[24:27], v[176:179], v[192:195], 0
	v_mfma_f32_16x16x32_bf16 v[12:15], v[168:171], v[200:203], 0
	v_mfma_f32_16x16x32_bf16 v[8:11], v[176:179], v[200:203], 0
	v_mfma_f32_16x16x32_bf16 v[4:7], v[168:171], v[208:211], 0
	v_mfma_f32_16x16x32_bf16 v[0:3], v[176:179], v[208:211], 0
	v_mfma_f32_16x16x32_bf16 v[44:47], v[172:175], v[188:191], v[44:47]
	v_mfma_f32_16x16x32_bf16 v[40:43], v[180:183], v[188:191], v[40:43]
	v_mfma_f32_16x16x32_bf16 v[28:31], v[172:175], v[196:199], v[28:31]
	v_mfma_f32_16x16x32_bf16 v[24:27], v[180:183], v[196:199], v[24:27]
	v_mfma_f32_16x16x32_bf16 v[12:15], v[172:175], v[204:207], v[12:15]
	v_mfma_f32_16x16x32_bf16 v[8:11], v[180:183], v[204:207], v[8:11]
	v_mfma_f32_16x16x32_bf16 v[4:7], v[172:175], v[212:215], v[4:7]
	v_mfma_f32_16x16x32_bf16 v[0:3], v[180:183], v[212:215], v[0:3]
	s_setprio 0
	s_barrier
	s_add_i32 s47, 0, 0x18000
	v_add_u32_e32 v151, s47, v146
	s_add_i32 s48, 0, 0x1c000
	ds_read_b128 v[152:155], v151
	ds_read_b128 v[156:159], v151 offset:1024
	ds_read_b128 v[160:163], v151 offset:2048
	ds_read_b128 v[164:167], v151 offset:3072
	v_add_u32_e32 v151, s48, v146
	ds_read_b128 v[168:171], v151
	ds_read_b128 v[172:175], v151 offset:1024
	ds_read_b128 v[176:179], v151 offset:2048
	ds_read_b128 v[180:183], v151 offset:3072
	s_add_u32 s22, s22, 0x40000
	s_addc_u32 s23, s23, 0
	s_mov_b32 m0, s30
	ds_read_b128 v[184:187], v150 offset:32768
	ds_read_b128 v[188:191], v150 offset:33792
	ds_read_b128 v[192:195], v150 offset:34816
	ds_read_b128 v[196:199], v150 offset:35840
	ds_read_b128 v[200:203], v150 offset:36864
	ds_read_b128 v[204:207], v150 offset:37888
	ds_read_b128 v[208:211], v150 offset:38912
	ds_read_b128 v[212:215], v150 offset:39936
	global_load_lds_dwordx4 v134, s[22:23]
	s_mov_b32 m0, s31
	s_nop 0
	global_load_lds_dwordx4 v130, s[22:23]
	s_waitcnt vmcnt(8)
	s_waitcnt lgkmcnt(0)
	s_barrier
	s_setprio 1
	s_waitcnt lgkmcnt(0)
	v_mfma_f32_16x16x32_bf16 v[124:127], v[152:155], v[184:187], v[124:127]
	v_mfma_f32_16x16x32_bf16 v[120:123], v[160:163], v[184:187], v[120:123]
	v_mfma_f32_16x16x32_bf16 v[116:119], v[152:155], v[192:195], v[116:119]
	v_mfma_f32_16x16x32_bf16 v[112:115], v[160:163], v[192:195], v[112:115]
	v_mfma_f32_16x16x32_bf16 v[100:103], v[152:155], v[200:203], v[100:103]
	v_mfma_f32_16x16x32_bf16 v[96:99], v[160:163], v[200:203], v[96:99]
	v_mfma_f32_16x16x32_bf16 v[84:87], v[152:155], v[208:211], v[84:87]
	v_mfma_f32_16x16x32_bf16 v[80:83], v[160:163], v[208:211], v[80:83]
	v_mfma_f32_16x16x32_bf16 v[124:127], v[156:159], v[188:191], v[124:127]
	v_mfma_f32_16x16x32_bf16 v[120:123], v[164:167], v[188:191], v[120:123]
	v_mfma_f32_16x16x32_bf16 v[116:119], v[156:159], v[196:199], v[116:119]
	v_mfma_f32_16x16x32_bf16 v[112:115], v[164:167], v[196:199], v[112:115]
	v_mfma_f32_16x16x32_bf16 v[100:103], v[156:159], v[204:207], v[100:103]
	v_mfma_f32_16x16x32_bf16 v[96:99], v[164:167], v[204:207], v[96:99]
	v_mfma_f32_16x16x32_bf16 v[84:87], v[156:159], v[212:215], v[84:87]
	v_mfma_f32_16x16x32_bf16 v[80:83], v[164:167], v[212:215], v[80:83]
	s_setprio 0
	s_setprio 1
	v_mfma_f32_16x16x32_bf16 v[108:111], v[168:171], v[184:187], v[108:111]
	v_mfma_f32_16x16x32_bf16 v[104:107], v[176:179], v[184:187], v[104:107]
	v_mfma_f32_16x16x32_bf16 v[92:95], v[168:171], v[192:195], v[92:95]
	v_mfma_f32_16x16x32_bf16 v[88:91], v[176:179], v[192:195], v[88:91]
	v_mfma_f32_16x16x32_bf16 v[76:79], v[168:171], v[200:203], v[76:79]
	v_mfma_f32_16x16x32_bf16 v[72:75], v[176:179], v[200:203], v[72:75]
	v_mfma_f32_16x16x32_bf16 v[68:71], v[168:171], v[208:211], v[68:71]
	v_mfma_f32_16x16x32_bf16 v[64:67], v[176:179], v[208:211], v[64:67]
	v_mfma_f32_16x16x32_bf16 v[108:111], v[172:175], v[188:191], v[108:111]
	v_mfma_f32_16x16x32_bf16 v[104:107], v[180:183], v[188:191], v[104:107]
	v_mfma_f32_16x16x32_bf16 v[92:95], v[172:175], v[196:199], v[92:95]
	v_mfma_f32_16x16x32_bf16 v[88:91], v[180:183], v[196:199], v[88:91]
	v_mfma_f32_16x16x32_bf16 v[76:79], v[172:175], v[204:207], v[76:79]
	v_mfma_f32_16x16x32_bf16 v[72:75], v[180:183], v[204:207], v[72:75]
	v_mfma_f32_16x16x32_bf16 v[68:71], v[172:175], v[212:215], v[68:71]
	v_mfma_f32_16x16x32_bf16 v[64:67], v[180:183], v[212:215], v[64:67]
	s_setprio 0
	s_barrier
	s_add_i32 s22, s47, s26
	s_mov_b32 m0, s22
	ds_read_b128 v[184:187], v150 offset:49152
	ds_read_b128 v[188:191], v150 offset:50176
	ds_read_b128 v[192:195], v150 offset:51200
	ds_read_b128 v[196:199], v150 offset:52224
	ds_read_b128 v[200:203], v150 offset:53248
	ds_read_b128 v[204:207], v150 offset:54272
	ds_read_b128 v[208:211], v150 offset:55296
	ds_read_b128 v[212:215], v150 offset:56320
	global_load_lds_dwordx4 v132, s[84:85]
	s_add_i32 m0, s22, 0x2000
	s_add_u32 s20, s20, 0x40080
	s_addc_u32 s21, s21, 0
	s_add_i32 s22, s48, s26
	global_load_lds_dwordx4 v128, s[84:85]
	s_mov_b32 m0, s22
	s_nop 0
	global_load_lds_dwordx4 v132, s[20:21]
	s_add_i32 m0, s22, 0x2000
	s_nop 0
	global_load_lds_dwordx4 v128, s[20:21]
	s_mov_b32 m0, s34
	s_nop 0
	global_load_lds_dwordx4 v134, s[86:87]
	s_mov_b32 m0, s35
	s_nop 0
	global_load_lds_dwordx4 v130, s[86:87]
	s_waitcnt vmcnt(8)
	s_waitcnt lgkmcnt(0)
	s_barrier
	s_setprio 1
	s_waitcnt lgkmcnt(0)
	v_mfma_f32_16x16x32_bf16 v[60:63], v[152:155], v[184:187], v[60:63]
	v_mfma_f32_16x16x32_bf16 v[56:59], v[160:163], v[184:187], v[56:59]
	v_mfma_f32_16x16x32_bf16 v[52:55], v[152:155], v[192:195], v[52:55]
	v_mfma_f32_16x16x32_bf16 v[48:51], v[160:163], v[192:195], v[48:51]
	v_mfma_f32_16x16x32_bf16 v[36:39], v[152:155], v[200:203], v[36:39]
	v_mfma_f32_16x16x32_bf16 v[32:35], v[160:163], v[200:203], v[32:35]
	v_mfma_f32_16x16x32_bf16 v[20:23], v[152:155], v[208:211], v[20:23]
	v_mfma_f32_16x16x32_bf16 v[16:19], v[160:163], v[208:211], v[16:19]
	v_mfma_f32_16x16x32_bf16 v[60:63], v[156:159], v[188:191], v[60:63]
	v_mfma_f32_16x16x32_bf16 v[56:59], v[164:167], v[188:191], v[56:59]
	v_mfma_f32_16x16x32_bf16 v[52:55], v[156:159], v[196:199], v[52:55]
	v_mfma_f32_16x16x32_bf16 v[48:51], v[164:167], v[196:199], v[48:51]
	v_mfma_f32_16x16x32_bf16 v[36:39], v[156:159], v[204:207], v[36:39]
	v_mfma_f32_16x16x32_bf16 v[32:35], v[164:167], v[204:207], v[32:35]
	v_mfma_f32_16x16x32_bf16 v[20:23], v[156:159], v[212:215], v[20:23]
	v_mfma_f32_16x16x32_bf16 v[16:19], v[164:167], v[212:215], v[16:19]
	s_setprio 0
	s_setprio 1
	v_mfma_f32_16x16x32_bf16 v[44:47], v[168:171], v[184:187], v[44:47]
	v_mfma_f32_16x16x32_bf16 v[40:43], v[176:179], v[184:187], v[40:43]
	v_mfma_f32_16x16x32_bf16 v[28:31], v[168:171], v[192:195], v[28:31]
	v_mfma_f32_16x16x32_bf16 v[24:27], v[176:179], v[192:195], v[24:27]
	v_mfma_f32_16x16x32_bf16 v[12:15], v[168:171], v[200:203], v[12:15]
	v_mfma_f32_16x16x32_bf16 v[8:11], v[176:179], v[200:203], v[8:11]
	v_mfma_f32_16x16x32_bf16 v[4:7], v[168:171], v[208:211], v[4:7]
	v_mfma_f32_16x16x32_bf16 v[0:3], v[176:179], v[208:211], v[0:3]
	v_mfma_f32_16x16x32_bf16 v[44:47], v[172:175], v[188:191], v[44:47]
	v_mfma_f32_16x16x32_bf16 v[40:43], v[180:183], v[188:191], v[40:43]
	v_mfma_f32_16x16x32_bf16 v[28:31], v[172:175], v[196:199], v[28:31]
	v_mfma_f32_16x16x32_bf16 v[24:27], v[180:183], v[196:199], v[24:27]
	v_mfma_f32_16x16x32_bf16 v[12:15], v[172:175], v[204:207], v[12:15]
	v_mfma_f32_16x16x32_bf16 v[8:11], v[180:183], v[204:207], v[8:11]
	v_mfma_f32_16x16x32_bf16 v[4:7], v[172:175], v[212:215], v[4:7]
	v_mfma_f32_16x16x32_bf16 v[0:3], v[180:183], v[212:215], v[0:3]
	s_setprio 0
	s_barrier
	s_add_i32 s46, s46, 2
	s_add_u32 s18, s18, 0x100
	s_addc_u32 s19, s19, 0
	s_add_u32 s44, s44, 0x100
	s_addc_u32 s45, s45, 0
	.p2alignl 6, 3212836864

.LBB0_364:
	v_and_b32_e32 v233, 15, v164
	v_and_b32_e32 v14, 48, v164
	v_lshlrev_b32_e32 v15, 2, v164
	s_and_b32 s43, s46, 3
	s_lshl_b32 s26, s42, 13
	v_lshl_or_b32 v14, v233, 6, v14
	v_and_b32_e32 v15, 32, v15
	s_add_i32 m0, s23, 0x18000
	v_lshl_add_u64 v[6:7], v[6:7], 0, s[34:35]
	v_bitop3_b32 v16, v14, s26, v15 bitop3:0xde
	s_lshl_b32 s26, s43, 12
	s_waitcnt vmcnt(2)
	s_barrier
	global_load_lds_dwordx4 v[6:7], off
	v_lshl_add_u64 v[4:5], v[4:5], 0, s[34:35]
	s_add_i32 m0, s23, 0x1a000
	s_add_i32 s58, s23, 0x8000
	s_add_i32 s59, s23, 0xa000
	v_bitop3_b32 v122, v14, s26, v15 bitop3:0xde
	global_load_lds_dwordx4 v[4:5], off
	v_lshl_add_u64 v[2:3], v[2:3], 0, s[34:35]
	s_mov_b32 m0, s58
	s_add_u32 s26, s0, 0x40080
	global_load_lds_dwordx4 v[2:3], off
	v_lshl_add_u64 v[0:1], v[0:1], 0, s[34:35]
	s_mov_b32 m0, s59
	s_addc_u32 s27, s1, 0
	global_load_lds_dwordx4 v[0:1], off
	s_add_i32 m0, s23, 0x1c000
	v_lshl_add_u64 v[0:1], s[26:27], 0, v[212:213]
	global_load_lds_dwordx4 v[0:1], off
	v_lshl_add_u64 v[0:1], s[26:27], 0, v[100:101]
	s_add_i32 m0, s23, 0x1e000
	s_add_u32 s60, s82, s10
	global_load_lds_dwordx4 v[0:1], off
	v_lshlrev_b32_e32 v0, 14, v12
	v_and_b32_e32 v0, 0xffff8000, v0
	s_addc_u32 s61, s83, s11
	v_lshl_add_u32 v0, v11, 11, v0
	v_and_b32_e32 v1, 1, v12
	v_lshl_or_b32 v0, v1, 6, v0
	s_add_u32 s10, s52, s10
	v_lshl_add_u32 v0, v13, 1, v0
	v_mov_b32_e32 v1, v213
	s_addc_u32 s11, s53, s11
	v_lshl_add_u64 v[110:111], s[10:11], 0, v[0:1]
	v_lshlrev_b32_e32 v0, 14, v8
	v_and_b32_e32 v0, 0xffff8000, v0
	v_lshl_add_u32 v0, v9, 11, v0
	v_and_b32_e32 v1, 1, v8
	v_lshl_or_b32 v0, v1, 6, v0
	v_lshl_add_u32 v0, v10, 1, v0
	v_mov_b32_e32 v1, v213
	v_lshl_add_u64 v[120:121], s[10:11], 0, v[0:1]
	s_add_u32 s62, s54, s8
	v_mov_b32_e32 v0, 0
	v_lshl_or_b32 v237, s42, 6, v233
	s_addc_u32 s63, s55, s9
	s_mov_b32 s64, -2
	s_mov_b64 s[8:9], 0
	v_add_u32_e32 v123, 0, v16
	v_mov_b32_e32 v1, v0
	v_mov_b32_e32 v2, v0
	v_mov_b32_e32 v3, v0
	v_mov_b32_e32 v4, v0
	v_mov_b32_e32 v5, v0
	v_mov_b32_e32 v6, v0
	v_mov_b32_e32 v7, v0
	v_mov_b32_e32 v16, v0
	v_mov_b32_e32 v17, v0
	v_mov_b32_e32 v18, v0
	v_mov_b32_e32 v19, v0
	v_mov_b32_e32 v20, v0
	v_mov_b32_e32 v21, v0
	v_mov_b32_e32 v22, v0
	v_mov_b32_e32 v23, v0
	v_mov_b32_e32 v32, v0
	v_mov_b32_e32 v33, v0
	v_mov_b32_e32 v34, v0
	v_mov_b32_e32 v35, v0
	v_mov_b32_e32 v36, v0
	v_mov_b32_e32 v37, v0
	v_mov_b32_e32 v38, v0
	v_mov_b32_e32 v39, v0
	v_mov_b32_e32 v48, v0
	v_mov_b32_e32 v49, v0
	v_mov_b32_e32 v50, v0
	v_mov_b32_e32 v51, v0
	v_mov_b32_e32 v52, v0
	v_mov_b32_e32 v53, v0
	v_mov_b32_e32 v54, v0
	v_mov_b32_e32 v55, v0
	v_mov_b32_e32 v8, v0
	v_mov_b32_e32 v9, v0
	v_mov_b32_e32 v10, v0
	v_mov_b32_e32 v11, v0
	v_mov_b32_e32 v12, v0
	v_mov_b32_e32 v13, v0
	v_mov_b32_e32 v14, v0
	v_mov_b32_e32 v15, v0
	v_mov_b32_e32 v24, v0
	v_mov_b32_e32 v25, v0
	v_mov_b32_e32 v26, v0
	v_mov_b32_e32 v27, v0
	v_mov_b32_e32 v28, v0
	v_mov_b32_e32 v29, v0
	v_mov_b32_e32 v30, v0
	v_mov_b32_e32 v31, v0
	v_mov_b32_e32 v40, v0
	v_mov_b32_e32 v41, v0
	v_mov_b32_e32 v42, v0
	v_mov_b32_e32 v43, v0
	v_mov_b32_e32 v44, v0
	v_mov_b32_e32 v45, v0
	v_mov_b32_e32 v46, v0
	v_mov_b32_e32 v47, v0
	v_mov_b32_e32 v56, v0
	v_mov_b32_e32 v57, v0
	v_mov_b32_e32 v58, v0
	v_mov_b32_e32 v59, v0
	v_mov_b32_e32 v60, v0
	v_mov_b32_e32 v61, v0
	v_mov_b32_e32 v62, v0
	v_mov_b32_e32 v63, v0
	v_mov_b32_e32 v64, v0
	v_mov_b32_e32 v65, v0
	v_mov_b32_e32 v66, v0
	v_mov_b32_e32 v67, v0
	v_mov_b32_e32 v68, v0
	v_mov_b32_e32 v69, v0
	v_mov_b32_e32 v70, v0
	v_mov_b32_e32 v71, v0
	v_mov_b32_e32 v80, v0
	v_mov_b32_e32 v81, v0
	v_mov_b32_e32 v82, v0
	v_mov_b32_e32 v83, v0
	v_mov_b32_e32 v84, v0
	v_mov_b32_e32 v85, v0
	v_mov_b32_e32 v86, v0
	v_mov_b32_e32 v87, v0
	v_mov_b32_e32 v96, v0
	v_mov_b32_e32 v97, v0
	v_mov_b32_e32 v98, v0
	v_mov_b32_e32 v99, v0
	v_mov_b32_e32 v104, v0
	v_mov_b32_e32 v105, v0
	v_mov_b32_e32 v106, v0
	v_mov_b32_e32 v107, v0
	v_mov_b32_e32 v136, v0
	v_mov_b32_e32 v137, v0
	v_mov_b32_e32 v138, v0
	v_mov_b32_e32 v139, v0
	v_mov_b32_e32 v140, v0
	v_mov_b32_e32 v141, v0
	v_mov_b32_e32 v142, v0
	v_mov_b32_e32 v143, v0
	v_mov_b32_e32 v72, v0
	v_mov_b32_e32 v73, v0
	v_mov_b32_e32 v74, v0
	v_mov_b32_e32 v75, v0
	v_mov_b32_e32 v76, v0
	v_mov_b32_e32 v77, v0
	v_mov_b32_e32 v78, v0
	v_mov_b32_e32 v79, v0
	v_mov_b32_e32 v88, v0
	v_mov_b32_e32 v89, v0
	v_mov_b32_e32 v90, v0
	v_mov_b32_e32 v91, v0
	v_mov_b32_e32 v92, v0
	v_mov_b32_e32 v93, v0
	v_mov_b32_e32 v94, v0
	v_mov_b32_e32 v95, v0
	v_mov_b32_e32 v112, v0
	v_mov_b32_e32 v113, v0
	v_mov_b32_e32 v114, v0
	v_mov_b32_e32 v115, v0
	v_mov_b32_e32 v116, v0
	v_mov_b32_e32 v117, v0
	v_mov_b32_e32 v118, v0
	v_mov_b32_e32 v119, v0
	v_mov_b32_e32 v152, v0
	v_mov_b32_e32 v153, v0
	v_mov_b32_e32 v154, v0
	v_mov_b32_e32 v155, v0
	v_mov_b32_e32 v156, v0
	v_mov_b32_e32 v157, v0
	v_mov_b32_e32 v158, v0
	v_mov_b32_e32 v159, v0
	s_waitcnt vmcnt(6)
	s_barrier
	.p2alignl 6, 3212836864

.LBB0_498:
	v_add_u32_e32 v188, s46, v165
	v_add_u32_e32 v204, s47, v165
	ds_read_b128 v[176:179], v188
	ds_read_b128 v[180:183], v188 offset:1024
	ds_read_b128 v[184:187], v188 offset:2048
	ds_read_b128 v[188:191], v188 offset:3072
	ds_read_b128 v[192:195], v204
	ds_read_b128 v[196:199], v204 offset:1024
	ds_read_b128 v[200:203], v204 offset:2048
	ds_read_b128 v[204:207], v204 offset:3072
	s_add_u32 s30, s26, 0xfffc0080
	s_addc_u32 s31, s27, -1
	s_and_b64 s[28:29], s[28:29], exec
	s_cselect_b32 s31, s11, s31
	s_cselect_b32 s30, s49, s30
	s_cselect_b32 s29, s9, s52
	s_cselect_b32 s28, s50, s51
	s_add_i32 m0, s36, 0xc000
	ds_read_b128 v[208:211], v167
	ds_read_b128 v[212:215], v167 offset:1024
	ds_read_b128 v[216:219], v167 offset:2048
	ds_read_b128 v[220:223], v167 offset:3072
	ds_read_b128 v[224:227], v167 offset:4096
	ds_read_b128 v[230:233], v167 offset:5120
	ds_read_b128 v[234:237], v167 offset:6144
	ds_read_b128 v[238:241], v167 offset:7168
	global_load_lds_dwordx4 v136, s[26:27]
	s_add_i32 m0, s36, 0xe000
	s_nop 0
	global_load_lds_dwordx4 v138, s[26:27]
	s_waitcnt vmcnt(8)
	s_waitcnt lgkmcnt(0)
	s_barrier
	s_setprio 1
	s_waitcnt lgkmcnt(0)
	v_mfma_f32_16x16x32_bf16 v[124:127], v[176:179], v[208:211], v[124:127]
	v_mfma_f32_16x16x32_bf16 v[120:123], v[184:187], v[208:211], v[120:123]
	v_mfma_f32_16x16x32_bf16 v[108:111], v[176:179], v[216:219], v[108:111]
	v_mfma_f32_16x16x32_bf16 v[104:107], v[184:187], v[216:219], v[104:107]
	v_mfma_f32_16x16x32_bf16 v[92:95], v[176:179], v[224:227], v[92:95]
	v_mfma_f32_16x16x32_bf16 v[88:91], v[184:187], v[224:227], v[88:91]
	v_mfma_f32_16x16x32_bf16 v[76:79], v[176:179], v[234:237], v[76:79]
	v_mfma_f32_16x16x32_bf16 v[72:75], v[184:187], v[234:237], v[72:75]
	v_mfma_f32_16x16x32_bf16 v[124:127], v[180:183], v[212:215], v[124:127]
	v_mfma_f32_16x16x32_bf16 v[120:123], v[188:191], v[212:215], v[120:123]
	v_mfma_f32_16x16x32_bf16 v[108:111], v[180:183], v[220:223], v[108:111]
	v_mfma_f32_16x16x32_bf16 v[104:107], v[188:191], v[220:223], v[104:107]
	v_mfma_f32_16x16x32_bf16 v[92:95], v[180:183], v[230:233], v[92:95]
	v_mfma_f32_16x16x32_bf16 v[88:91], v[188:191], v[230:233], v[88:91]
	v_mfma_f32_16x16x32_bf16 v[76:79], v[180:183], v[238:241], v[76:79]
	v_mfma_f32_16x16x32_bf16 v[72:75], v[188:191], v[238:241], v[72:75]
	s_setprio 0
	s_setprio 1
	v_mfma_f32_16x16x32_bf16 v[116:119], v[192:195], v[208:211], v[116:119]
	v_mfma_f32_16x16x32_bf16 v[112:115], v[200:203], v[208:211], v[112:115]
	v_mfma_f32_16x16x32_bf16 v[100:103], v[192:195], v[216:219], v[100:103]
	v_mfma_f32_16x16x32_bf16 v[96:99], v[200:203], v[216:219], v[96:99]
	v_mfma_f32_16x16x32_bf16 v[84:87], v[192:195], v[224:227], v[84:87]
	v_mfma_f32_16x16x32_bf16 v[80:83], v[200:203], v[224:227], v[80:83]
	v_mfma_f32_16x16x32_bf16 v[68:71], v[192:195], v[234:237], v[68:71]
	v_mfma_f32_16x16x32_bf16 v[64:67], v[200:203], v[234:237], v[64:67]
	v_mfma_f32_16x16x32_bf16 v[116:119], v[196:199], v[212:215], v[116:119]
	v_mfma_f32_16x16x32_bf16 v[112:115], v[204:207], v[212:215], v[112:115]
	v_mfma_f32_16x16x32_bf16 v[100:103], v[196:199], v[220:223], v[100:103]
	v_mfma_f32_16x16x32_bf16 v[96:99], v[204:207], v[220:223], v[96:99]
	v_mfma_f32_16x16x32_bf16 v[84:87], v[196:199], v[230:233], v[84:87]
	v_mfma_f32_16x16x32_bf16 v[80:83], v[204:207], v[230:233], v[80:83]
	v_mfma_f32_16x16x32_bf16 v[68:71], v[196:199], v[238:241], v[68:71]
	v_mfma_f32_16x16x32_bf16 v[64:67], v[204:207], v[238:241], v[64:67]
	s_setprio 0
	s_barrier
	s_add_i32 s54, s46, s35
	s_mov_b32 m0, s54
	ds_read_b128 v[208:211], v167 offset:16384
	ds_read_b128 v[212:215], v167 offset:17408
	ds_read_b128 v[216:219], v167 offset:18432
	ds_read_b128 v[220:223], v167 offset:19456
	ds_read_b128 v[224:227], v167 offset:20480
	ds_read_b128 v[230:233], v167 offset:21504
	ds_read_b128 v[234:237], v167 offset:22528
	ds_read_b128 v[238:241], v167 offset:23552
	global_load_lds_dwordx4 v130, s[28:29]
	s_add_i32 m0, s54, 0x2000
	s_add_u32 s54, s28, 0x40000
	s_addc_u32 s55, s29, 0
	s_add_i32 s56, s47, s35
	global_load_lds_dwordx4 v134, s[28:29]
	s_mov_b32 m0, s56
	s_nop 0
	global_load_lds_dwordx4 v130, s[54:55]
	s_add_i32 m0, s56, 0x2000
	s_nop 0
	global_load_lds_dwordx4 v134, s[54:55]
	s_mov_b32 m0, s36
	s_nop 0
	global_load_lds_dwordx4 v128, s[30:31]
	s_mov_b32 m0, s37
	s_nop 0
	global_load_lds_dwordx4 v132, s[30:31]
	s_add_u32 s86, s30, s4
	s_addc_u32 s87, s31, s5
	s_add_u32 s84, s28, s4
	s_addc_u32 s85, s29, s5
	s_waitcnt vmcnt(8)
	s_waitcnt lgkmcnt(0)
	s_barrier
	s_setprio 1
	s_waitcnt lgkmcnt(0)
	v_mfma_f32_16x16x32_bf16 v[60:63], v[176:179], v[208:211], v[60:63]
	v_mfma_f32_16x16x32_bf16 v[56:59], v[184:187], v[208:211], v[56:59]
	v_mfma_f32_16x16x32_bf16 v[44:47], v[176:179], v[216:219], v[44:47]
	v_mfma_f32_16x16x32_bf16 v[40:43], v[184:187], v[216:219], v[40:43]
	v_mfma_f32_16x16x32_bf16 v[28:31], v[176:179], v[224:227], v[28:31]
	v_mfma_f32_16x16x32_bf16 v[24:27], v[184:187], v[224:227], v[24:27]
	v_mfma_f32_16x16x32_bf16 v[12:15], v[176:179], v[234:237], v[12:15]
	v_mfma_f32_16x16x32_bf16 v[8:11], v[184:187], v[234:237], v[8:11]
	v_mfma_f32_16x16x32_bf16 v[60:63], v[180:183], v[212:215], v[60:63]
	v_mfma_f32_16x16x32_bf16 v[56:59], v[188:191], v[212:215], v[56:59]
	v_mfma_f32_16x16x32_bf16 v[44:47], v[180:183], v[220:223], v[44:47]
	v_mfma_f32_16x16x32_bf16 v[40:43], v[188:191], v[220:223], v[40:43]
	v_mfma_f32_16x16x32_bf16 v[28:31], v[180:183], v[230:233], v[28:31]
	v_mfma_f32_16x16x32_bf16 v[24:27], v[188:191], v[230:233], v[24:27]
	v_mfma_f32_16x16x32_bf16 v[12:15], v[180:183], v[238:241], v[12:15]
	v_mfma_f32_16x16x32_bf16 v[8:11], v[188:191], v[238:241], v[8:11]
	s_setprio 0
	s_setprio 1
	v_mfma_f32_16x16x32_bf16 v[52:55], v[192:195], v[208:211], v[52:55]
	v_mfma_f32_16x16x32_bf16 v[48:51], v[200:203], v[208:211], v[48:51]
	v_mfma_f32_16x16x32_bf16 v[36:39], v[192:195], v[216:219], v[36:39]
	v_mfma_f32_16x16x32_bf16 v[32:35], v[200:203], v[216:219], v[32:35]
	v_mfma_f32_16x16x32_bf16 v[20:23], v[192:195], v[224:227], v[20:23]
	v_mfma_f32_16x16x32_bf16 v[16:19], v[200:203], v[224:227], v[16:19]
	v_mfma_f32_16x16x32_bf16 v[4:7], v[192:195], v[234:237], v[4:7]
	v_mfma_f32_16x16x32_bf16 v[0:3], v[200:203], v[234:237], v[0:3]
	v_mfma_f32_16x16x32_bf16 v[52:55], v[196:199], v[212:215], v[52:55]
	v_mfma_f32_16x16x32_bf16 v[48:51], v[204:207], v[212:215], v[48:51]
	v_mfma_f32_16x16x32_bf16 v[36:39], v[196:199], v[220:223], v[36:39]
	v_mfma_f32_16x16x32_bf16 v[32:35], v[204:207], v[220:223], v[32:35]
	v_mfma_f32_16x16x32_bf16 v[20:23], v[196:199], v[230:233], v[20:23]
	v_mfma_f32_16x16x32_bf16 v[16:19], v[204:207], v[230:233], v[16:19]
	v_mfma_f32_16x16x32_bf16 v[4:7], v[196:199], v[238:241], v[4:7]
	v_mfma_f32_16x16x32_bf16 v[0:3], v[204:207], v[238:241], v[0:3]
	s_setprio 0
	s_barrier
	s_add_i32 s54, 0, 0x18000
	s_add_i32 s55, 0, 0x1c000
	v_add_u32_e32 v188, s54, v165
	v_add_u32_e32 v204, s55, v165
	ds_read_b128 v[176:179], v188
	ds_read_b128 v[180:183], v188 offset:1024
	ds_read_b128 v[184:187], v188 offset:2048
	ds_read_b128 v[188:191], v188 offset:3072
	ds_read_b128 v[192:195], v204
	ds_read_b128 v[196:199], v204 offset:1024
	ds_read_b128 v[200:203], v204 offset:2048
	ds_read_b128 v[204:207], v204 offset:3072
	s_add_u32 s30, s30, 0x40000
	s_addc_u32 s31, s31, 0
	s_mov_b32 m0, s41
	ds_read_b128 v[208:211], v167 offset:32768
	ds_read_b128 v[212:215], v167 offset:33792
	ds_read_b128 v[216:219], v167 offset:34816
	ds_read_b128 v[220:223], v167 offset:35840
	ds_read_b128 v[224:227], v167 offset:36864
	ds_read_b128 v[230:233], v167 offset:37888
	ds_read_b128 v[234:237], v167 offset:38912
	ds_read_b128 v[238:241], v167 offset:39936
	global_load_lds_dwordx4 v128, s[30:31]
	s_mov_b32 m0, s42
	s_nop 0
	global_load_lds_dwordx4 v132, s[30:31]
	s_waitcnt vmcnt(8)
	s_waitcnt lgkmcnt(0)
	s_barrier
	s_setprio 1
	s_waitcnt lgkmcnt(0)
	v_mfma_f32_16x16x32_bf16 v[124:127], v[176:179], v[208:211], v[124:127]
	v_mfma_f32_16x16x32_bf16 v[120:123], v[184:187], v[208:211], v[120:123]
	v_mfma_f32_16x16x32_bf16 v[108:111], v[176:179], v[216:219], v[108:111]
	v_mfma_f32_16x16x32_bf16 v[104:107], v[184:187], v[216:219], v[104:107]
	v_mfma_f32_16x16x32_bf16 v[92:95], v[176:179], v[224:227], v[92:95]
	v_mfma_f32_16x16x32_bf16 v[88:91], v[184:187], v[224:227], v[88:91]
	v_mfma_f32_16x16x32_bf16 v[76:79], v[176:179], v[234:237], v[76:79]
	v_mfma_f32_16x16x32_bf16 v[72:75], v[184:187], v[234:237], v[72:75]
	v_mfma_f32_16x16x32_bf16 v[124:127], v[180:183], v[212:215], v[124:127]
	v_mfma_f32_16x16x32_bf16 v[120:123], v[188:191], v[212:215], v[120:123]
	v_mfma_f32_16x16x32_bf16 v[108:111], v[180:183], v[220:223], v[108:111]
	v_mfma_f32_16x16x32_bf16 v[104:107], v[188:191], v[220:223], v[104:107]
	v_mfma_f32_16x16x32_bf16 v[92:95], v[180:183], v[230:233], v[92:95]
	v_mfma_f32_16x16x32_bf16 v[88:91], v[188:191], v[230:233], v[88:91]
	v_mfma_f32_16x16x32_bf16 v[76:79], v[180:183], v[238:241], v[76:79]
	v_mfma_f32_16x16x32_bf16 v[72:75], v[188:191], v[238:241], v[72:75]
	s_setprio 0
	s_setprio 1
	v_mfma_f32_16x16x32_bf16 v[116:119], v[192:195], v[208:211], v[116:119]
	v_mfma_f32_16x16x32_bf16 v[112:115], v[200:203], v[208:211], v[112:115]
	v_mfma_f32_16x16x32_bf16 v[100:103], v[192:195], v[216:219], v[100:103]
	v_mfma_f32_16x16x32_bf16 v[96:99], v[200:203], v[216:219], v[96:99]
	v_mfma_f32_16x16x32_bf16 v[84:87], v[192:195], v[224:227], v[84:87]
	v_mfma_f32_16x16x32_bf16 v[80:83], v[200:203], v[224:227], v[80:83]
	v_mfma_f32_16x16x32_bf16 v[68:71], v[192:195], v[234:237], v[68:71]
	v_mfma_f32_16x16x32_bf16 v[64:67], v[200:203], v[234:237], v[64:67]
	v_mfma_f32_16x16x32_bf16 v[116:119], v[196:199], v[212:215], v[116:119]
	v_mfma_f32_16x16x32_bf16 v[112:115], v[204:207], v[212:215], v[112:115]
	v_mfma_f32_16x16x32_bf16 v[100:103], v[196:199], v[220:223], v[100:103]
	v_mfma_f32_16x16x32_bf16 v[96:99], v[204:207], v[220:223], v[96:99]
	v_mfma_f32_16x16x32_bf16 v[84:87], v[196:199], v[230:233], v[84:87]
	v_mfma_f32_16x16x32_bf16 v[80:83], v[204:207], v[230:233], v[80:83]
	v_mfma_f32_16x16x32_bf16 v[68:71], v[196:199], v[238:241], v[68:71]
	v_mfma_f32_16x16x32_bf16 v[64:67], v[204:207], v[238:241], v[64:67]
	s_setprio 0
	s_barrier
	s_add_i32 s30, s54, s35
	s_mov_b32 m0, s30
	ds_read_b128 v[208:211], v167 offset:49152
	ds_read_b128 v[212:215], v167 offset:50176
	ds_read_b128 v[216:219], v167 offset:51200
	ds_read_b128 v[220:223], v167 offset:52224
	ds_read_b128 v[224:227], v167 offset:53248
	ds_read_b128 v[230:233], v167 offset:54272
	ds_read_b128 v[234:237], v167 offset:55296
	ds_read_b128 v[238:241], v167 offset:56320
	global_load_lds_dwordx4 v130, s[84:85]
	s_add_i32 m0, s30, 0x2000
	s_add_u32 s28, s28, 0x40080
	s_addc_u32 s29, s29, 0
	s_add_i32 s30, s55, s35
	global_load_lds_dwordx4 v134, s[84:85]
	s_mov_b32 m0, s30
	s_nop 0
	global_load_lds_dwordx4 v130, s[28:29]
	s_add_i32 m0, s30, 0x2000
	s_nop 0
	global_load_lds_dwordx4 v134, s[28:29]
	s_mov_b32 m0, s44
	s_nop 0
	global_load_lds_dwordx4 v128, s[86:87]
	s_mov_b32 m0, s45
	s_nop 0
	global_load_lds_dwordx4 v132, s[86:87]
	s_waitcnt vmcnt(8)
	s_waitcnt lgkmcnt(0)
	s_barrier
	s_setprio 1
	s_waitcnt lgkmcnt(0)
	v_mfma_f32_16x16x32_bf16 v[60:63], v[176:179], v[208:211], v[60:63]
	v_mfma_f32_16x16x32_bf16 v[56:59], v[184:187], v[208:211], v[56:59]
	v_mfma_f32_16x16x32_bf16 v[44:47], v[176:179], v[216:219], v[44:47]
	v_mfma_f32_16x16x32_bf16 v[40:43], v[184:187], v[216:219], v[40:43]
	v_mfma_f32_16x16x32_bf16 v[28:31], v[176:179], v[224:227], v[28:31]
	v_mfma_f32_16x16x32_bf16 v[24:27], v[184:187], v[224:227], v[24:27]
	v_mfma_f32_16x16x32_bf16 v[12:15], v[176:179], v[234:237], v[12:15]
	v_mfma_f32_16x16x32_bf16 v[8:11], v[184:187], v[234:237], v[8:11]
	v_mfma_f32_16x16x32_bf16 v[60:63], v[180:183], v[212:215], v[60:63]
	v_mfma_f32_16x16x32_bf16 v[56:59], v[188:191], v[212:215], v[56:59]
	v_mfma_f32_16x16x32_bf16 v[44:47], v[180:183], v[220:223], v[44:47]
	v_mfma_f32_16x16x32_bf16 v[40:43], v[188:191], v[220:223], v[40:43]
	v_mfma_f32_16x16x32_bf16 v[28:31], v[180:183], v[230:233], v[28:31]
	v_mfma_f32_16x16x32_bf16 v[24:27], v[188:191], v[230:233], v[24:27]
	v_mfma_f32_16x16x32_bf16 v[12:15], v[180:183], v[238:241], v[12:15]
	v_mfma_f32_16x16x32_bf16 v[8:11], v[188:191], v[238:241], v[8:11]
	s_setprio 0
	s_setprio 1
	v_mfma_f32_16x16x32_bf16 v[52:55], v[192:195], v[208:211], v[52:55]
	v_mfma_f32_16x16x32_bf16 v[48:51], v[200:203], v[208:211], v[48:51]
	v_mfma_f32_16x16x32_bf16 v[36:39], v[192:195], v[216:219], v[36:39]
	v_mfma_f32_16x16x32_bf16 v[32:35], v[200:203], v[216:219], v[32:35]
	v_mfma_f32_16x16x32_bf16 v[20:23], v[192:195], v[224:227], v[20:23]
	v_mfma_f32_16x16x32_bf16 v[16:19], v[200:203], v[224:227], v[16:19]
	v_mfma_f32_16x16x32_bf16 v[4:7], v[192:195], v[234:237], v[4:7]
	v_mfma_f32_16x16x32_bf16 v[0:3], v[200:203], v[234:237], v[0:3]
	v_mfma_f32_16x16x32_bf16 v[52:55], v[196:199], v[212:215], v[52:55]
	v_mfma_f32_16x16x32_bf16 v[48:51], v[204:207], v[212:215], v[48:51]
	v_mfma_f32_16x16x32_bf16 v[36:39], v[196:199], v[220:223], v[36:39]
	v_mfma_f32_16x16x32_bf16 v[32:35], v[204:207], v[220:223], v[32:35]
	v_mfma_f32_16x16x32_bf16 v[20:23], v[196:199], v[230:233], v[20:23]
	v_mfma_f32_16x16x32_bf16 v[16:19], v[204:207], v[230:233], v[16:19]
	v_mfma_f32_16x16x32_bf16 v[4:7], v[196:199], v[238:241], v[4:7]
	v_mfma_f32_16x16x32_bf16 v[0:3], v[204:207], v[238:241], v[0:3]
	s_setprio 0
	s_barrier
	s_add_i32 s53, s53, 2
	s_add_u32 s26, s26, 0x100
	s_addc_u32 s27, s27, 0
	s_add_u32 s51, s51, 0x100
	s_addc_u32 s52, s52, 0
	s_cmp_gt_u32 s53, 13
	s_cbranch_scc1 .LBB0_501
	.p2alignl 6, 3212836864

.LBB0_598:
	v_and_b32_e32 v183, 15, v182
	v_and_b32_e32 v14, 48, v182
	v_lshlrev_b32_e32 v15, 2, v182
	s_and_b32 s3, s37, 3
	s_lshl_b32 s22, s41, 13
	v_lshl_or_b32 v14, v183, 6, v14
	v_and_b32_e32 v15, 32, v15
	s_add_i32 m0, s43, 0x18000
	v_lshl_add_u64 v[6:7], v[6:7], 0, s[4:5]
	s_lshl_b32 s47, s41, 6
	v_bitop3_b32 v16, v14, s22, v15 bitop3:0xde
	s_lshl_b32 s22, s3, 12
	s_waitcnt vmcnt(2)
	s_barrier
	global_load_lds_dwordx4 v[6:7], off
	v_lshl_add_u64 v[4:5], v[4:5], 0, s[4:5]
	s_add_i32 m0, s43, 0x1a000
	s_add_i32 s48, s43, 0x8000
	s_add_i32 s49, s43, 0xa000
	v_bitop3_b32 v138, v14, s22, v15 bitop3:0xde
	global_load_lds_dwordx4 v[4:5], off
	v_lshl_add_u64 v[2:3], v[2:3], 0, s[4:5]
	s_mov_b32 m0, s48
	s_add_u32 s22, s0, 0x100080
	global_load_lds_dwordx4 v[2:3], off
	v_lshl_add_u64 v[0:1], v[0:1], 0, s[4:5]
	s_mov_b32 m0, s49
	s_addc_u32 s23, s1, 0
	global_load_lds_dwordx4 v[0:1], off
	s_add_i32 m0, s43, 0x1c000
	v_lshl_add_u64 v[0:1], s[22:23], 0, v[212:213]
	global_load_lds_dwordx4 v[0:1], off
	v_lshl_add_u64 v[0:1], s[22:23], 0, v[128:129]
	s_add_i32 m0, s43, 0x1e000
	s_add_u32 s50, s82, s20
	global_load_lds_dwordx4 v[0:1], off
	v_lshlrev_b32_e32 v0, 16, v12
	v_and_b32_e32 v0, 0xfffe0000, v0
	s_addc_u32 s51, s83, s21
	v_lshl_add_u32 v0, v11, 13, v0
	v_and_b32_e32 v1, 1, v12
	v_lshl_or_b32 v0, v1, 6, v0
	s_add_u32 s20, s29, s20
	v_lshl_add_u32 v0, v13, 1, v0
	v_mov_b32_e32 v1, v213
	s_addc_u32 s21, s30, s21
	v_lshl_add_u64 v[134:135], s[20:21], 0, v[0:1]
	v_lshlrev_b32_e32 v0, 16, v8
	v_and_b32_e32 v0, 0xfffe0000, v0
	v_lshl_add_u32 v0, v9, 13, v0
	v_and_b32_e32 v1, 1, v8
	v_lshl_or_b32 v0, v1, 6, v0
	v_lshl_add_u32 v0, v10, 1, v0
	v_mov_b32_e32 v1, v213
	v_lshl_add_u64 v[136:137], s[20:21], 0, v[0:1]
	s_add_u32 s52, s31, s18
	v_mov_b32_e32 v0, 0
	v_or_b32_e32 v216, s47, v183
	s_addc_u32 s53, s33, s19
	s_mov_b32 s54, -2
	s_mov_b64 s[18:19], 0
	v_add_u32_e32 v139, 0, v16
	v_mov_b32_e32 v1, v0
	v_mov_b32_e32 v2, v0
	v_mov_b32_e32 v3, v0
	v_mov_b32_e32 v4, v0
	v_mov_b32_e32 v5, v0
	v_mov_b32_e32 v6, v0
	v_mov_b32_e32 v7, v0
	v_mov_b32_e32 v12, v0
	v_mov_b32_e32 v13, v0
	v_mov_b32_e32 v14, v0
	v_mov_b32_e32 v15, v0
	v_mov_b32_e32 v20, v0
	v_mov_b32_e32 v21, v0
	v_mov_b32_e32 v22, v0
	v_mov_b32_e32 v23, v0
	v_mov_b32_e32 v32, v0
	v_mov_b32_e32 v33, v0
	v_mov_b32_e32 v34, v0
	v_mov_b32_e32 v35, v0
	v_mov_b32_e32 v36, v0
	v_mov_b32_e32 v37, v0
	v_mov_b32_e32 v38, v0
	v_mov_b32_e32 v39, v0
	v_mov_b32_e32 v44, v0
	v_mov_b32_e32 v45, v0
	v_mov_b32_e32 v46, v0
	v_mov_b32_e32 v47, v0
	v_mov_b32_e32 v52, v0
	v_mov_b32_e32 v53, v0
	v_mov_b32_e32 v54, v0
	v_mov_b32_e32 v55, v0
	v_mov_b32_e32 v8, v0
	v_mov_b32_e32 v9, v0
	v_mov_b32_e32 v10, v0
	v_mov_b32_e32 v11, v0
	v_mov_b32_e32 v16, v0
	v_mov_b32_e32 v17, v0
	v_mov_b32_e32 v18, v0
	v_mov_b32_e32 v19, v0
	v_mov_b32_e32 v24, v0
	v_mov_b32_e32 v25, v0
	v_mov_b32_e32 v26, v0
	v_mov_b32_e32 v27, v0
	v_mov_b32_e32 v28, v0
	v_mov_b32_e32 v29, v0
	v_mov_b32_e32 v30, v0
	v_mov_b32_e32 v31, v0
	v_mov_b32_e32 v40, v0
	v_mov_b32_e32 v41, v0
	v_mov_b32_e32 v42, v0
	v_mov_b32_e32 v43, v0
	v_mov_b32_e32 v48, v0
	v_mov_b32_e32 v49, v0
	v_mov_b32_e32 v50, v0
	v_mov_b32_e32 v51, v0
	v_mov_b32_e32 v56, v0
	v_mov_b32_e32 v57, v0
	v_mov_b32_e32 v58, v0
	v_mov_b32_e32 v59, v0
	v_mov_b32_e32 v60, v0
	v_mov_b32_e32 v61, v0
	v_mov_b32_e32 v62, v0
	v_mov_b32_e32 v63, v0
	v_mov_b32_e32 v64, v0
	v_mov_b32_e32 v65, v0
	v_mov_b32_e32 v66, v0
	v_mov_b32_e32 v67, v0
	v_mov_b32_e32 v68, v0
	v_mov_b32_e32 v69, v0
	v_mov_b32_e32 v70, v0
	v_mov_b32_e32 v71, v0
	v_mov_b32_e32 v76, v0
	v_mov_b32_e32 v77, v0
	v_mov_b32_e32 v78, v0
	v_mov_b32_e32 v79, v0
	v_mov_b32_e32 v84, v0
	v_mov_b32_e32 v85, v0
	v_mov_b32_e32 v86, v0
	v_mov_b32_e32 v87, v0
	v_mov_b32_e32 v96, v0
	v_mov_b32_e32 v97, v0
	v_mov_b32_e32 v98, v0
	v_mov_b32_e32 v99, v0
	v_mov_b32_e32 v100, v0
	v_mov_b32_e32 v101, v0
	v_mov_b32_e32 v102, v0
	v_mov_b32_e32 v103, v0
	v_mov_b32_e32 v104, v0
	v_mov_b32_e32 v105, v0
	v_mov_b32_e32 v106, v0
	v_mov_b32_e32 v107, v0
	v_mov_b32_e32 v108, v0
	v_mov_b32_e32 v109, v0
	v_mov_b32_e32 v110, v0
	v_mov_b32_e32 v111, v0
	v_mov_b32_e32 v72, v0
	v_mov_b32_e32 v73, v0
	v_mov_b32_e32 v74, v0
	v_mov_b32_e32 v75, v0
	v_mov_b32_e32 v80, v0
	v_mov_b32_e32 v81, v0
	v_mov_b32_e32 v82, v0
	v_mov_b32_e32 v83, v0
	v_mov_b32_e32 v88, v0
	v_mov_b32_e32 v89, v0
	v_mov_b32_e32 v90, v0
	v_mov_b32_e32 v91, v0
	v_mov_b32_e32 v92, v0
	v_mov_b32_e32 v93, v0
	v_mov_b32_e32 v94, v0
	v_mov_b32_e32 v95, v0
	v_mov_b32_e32 v112, v0
	v_mov_b32_e32 v113, v0
	v_mov_b32_e32 v114, v0
	v_mov_b32_e32 v115, v0
	v_mov_b32_e32 v116, v0
	v_mov_b32_e32 v117, v0
	v_mov_b32_e32 v118, v0
	v_mov_b32_e32 v119, v0
	v_mov_b32_e32 v120, v0
	v_mov_b32_e32 v121, v0
	v_mov_b32_e32 v122, v0
	v_mov_b32_e32 v123, v0
	v_mov_b32_e32 v124, v0
	v_mov_b32_e32 v125, v0
	v_mov_b32_e32 v126, v0
	v_mov_b32_e32 v127, v0
	s_waitcnt vmcnt(6)
	s_barrier
	.p2alignl 6, 3212836864
